# Dilated / neighbourhood attention: first two V-fragment read pairs issued in the mandatory MFMA-to-VALU wait window after QK^T (replaces s_nop 9), hiding their LDS latency behind the softmax
# speedup vs baseline: 1.0006x; 1.0006x over previous
; template <int KSTEPS, class Pol>
; __device__ __forceinline__ void attn_pass(LAS unsigned char* lds, const Pol& P, const bf16_t* qb, int ldq, const bf16_t* kb, int ldk, const bf16_t* vb, int ldv,
;                                           float qs, f32x16 (&O)[4], float& m, float& l) {
;     ...
;     auto qk_softmax = [&](int st, int t) __attribute__((always_inline)) {
;         LAS unsigned char* Kb = lds + st * A_STAGE + krow;
;         f32x16 S0, S1;
;         P.fill(S0, S1, qi, half, t, wave);
; #pragma unroll
;         for (int ks = 0; ks < KSTEPS; ++ks) {
;             const int so = ((2 * ks) ^ kx) << 4;
;             const bf16x8 a0 = *(const LAS bf16x8*)(Kb + so);
;             const bf16x8 a1 = *(const LAS bf16x8*)(Kb + 32 * KROWB + so);
;             S0 = MFMA32(a0, qf[ks], S0);
;             S1 = MFMA32(a1, qf[ks], S1);
;         }
;         S0 = S0 * qs; S1 = S1 * qs;
;         float mx = fmaxf(S0[0], S1[0]);
; #pragma unroll
;         for (int i = 1; i < 16; ++i) mx = fmaxf(fmaxf(mx, S0[i]), S1[i]);
;         mx = fmaxf(mx, __shfl_xor(mx, 32));
;         const float mnew = fmaxf(m, mx);
;         const float alpha = __builtin_amdgcn_exp2f(m - mnew);
;         m = mnew;
;         {
;             const f32x2 nm = {-mnew, -mnew};
; #pragma unroll
;             for (int i = 0; i < 16; i += 2) { const f32x2 a = (f32x2){S0[i], S0[i + 1]} + nm, b = (f32x2){S1[i], S1[i + 1]} + nm; S0[i] = a.x; S0[i + 1] = a.y; S1[i] = b.x; S1[i + 1] = b.y; }
;         }
;         f32x2 ls2 = {0.f, 0.f};
; #pragma unroll
;         for (int s = 0; s < 4; ++s) {
;             unsigned w[4];
; #pragma unroll
;             for (int e = 0; e < 4; ++e) {
;                 const int i = 8 * (s & 1) + 2 * e;
;                 f32x2 pv;
;                 pv.x = __builtin_amdgcn_exp2f(s < 2 ? S0[i] : S1[i]); pv.y = __builtin_amdgcn_exp2f(s < 2 ? S0[i + 1] : S1[i + 1]);
;                 ls2 = ls2 + pv;
;                 w[e] = pk2(pv.x, pv.y);
;             }
;             u32x4 wv; wv.x = w[0]; wv.y = w[1]; wv.z = w[2]; wv.w = w[3];
;             pf[s] = __builtin_bit_cast(bf16x8, wv);
;         }
;         l = l * alpha + (ls2.x + ls2.y);
;         if (__any(alpha != 1.0f)) {
; #pragma unroll
;             for (int blk = 0; blk < 4; ++blk) O[blk] = O[blk] * alpha;
;         }
;     ...
;     auto pv_acc = [&](int st) __attribute__((always_inline)) {
.LBB0_237:
	s_lshl_b32 s44, s74, 15
	s_add_i32 s44, s44, 0
	v_add_u32_e32 v0, s44, v160
	v_add_u32_e32 v6, v0, v161
	ds_read_b128 v[2:5], v6
	ds_read_b128 v[6:9], v6 offset:8192
	v_add_u32_e32 v200, v0, v162
	ds_read_b128 v[192:195], v200
	ds_read_b128 v[196:199], v200 offset:8192
	v_and_b32_e32 v15, 64, v234
	v_xor_b32_e32 v14, 32, v234
	v_add_u32_e32 v15, 64, v15
	s_waitcnt lgkmcnt(3)
	v_mfma_f32_32x32x16_bf16 v[96:111], v[2:5], v[112:115], v[96:111]
	v_cmp_lt_i32_e32 vcc, v14, v15
	s_nop 1
	v_cndmask_b32_e32 v14, v234, v14, vcc
	v_lshlrev_b32_e32 v14, 2, v14
	s_waitcnt lgkmcnt(2)
	v_mfma_f32_32x32x16_bf16 v[80:95], v[6:9], v[112:115], v[80:95]
	v_add_u32_e32 v6, v0, v163
	ds_read_b128 v[2:5], v6
	ds_read_b128 v[6:9], v6 offset:8192
	s_waitcnt lgkmcnt(3)
	v_mfma_f32_32x32x16_bf16 v[96:111], v[192:195], v[116:119], v[96:111]
	s_waitcnt lgkmcnt(2)
	v_mfma_f32_32x32x16_bf16 v[80:95], v[196:199], v[116:119], v[80:95]
	v_add_u32_e32 v200, v0, v164
	ds_read_b128 v[192:195], v200
	ds_read_b128 v[196:199], v200 offset:8192
	s_waitcnt lgkmcnt(3)
	v_mfma_f32_32x32x16_bf16 v[96:111], v[2:5], v[120:123], v[96:111]
	s_waitcnt lgkmcnt(2)
	v_mfma_f32_32x32x16_bf16 v[80:95], v[6:9], v[120:123], v[80:95]
	v_add_u32_e32 v6, v0, v165
	ds_read_b128 v[2:5], v6
	ds_read_b128 v[6:9], v6 offset:8192
	s_waitcnt lgkmcnt(3)
	v_mfma_f32_32x32x16_bf16 v[96:111], v[192:195], v[124:127], v[96:111]
	s_waitcnt lgkmcnt(2)
	v_mfma_f32_32x32x16_bf16 v[80:95], v[196:199], v[124:127], v[80:95]
	v_add_u32_e32 v200, v0, v166
	ds_read_b128 v[192:195], v200
	ds_read_b128 v[196:199], v200 offset:8192
	s_waitcnt lgkmcnt(3)
	v_mfma_f32_32x32x16_bf16 v[96:111], v[2:5], v[128:131], v[96:111]
	s_waitcnt lgkmcnt(2)
	v_mfma_f32_32x32x16_bf16 v[80:95], v[6:9], v[128:131], v[80:95]
	v_add_u32_e32 v6, v0, v167
	ds_read_b128 v[2:5], v6
	ds_read_b128 v[6:9], v6 offset:8192
	s_waitcnt lgkmcnt(3)
	v_mfma_f32_32x32x16_bf16 v[96:111], v[192:195], v[132:135], v[96:111]
	s_waitcnt lgkmcnt(2)
	v_mfma_f32_32x32x16_bf16 v[80:95], v[196:199], v[132:135], v[80:95]
	v_add_u32_e32 v200, v0, v168
	ds_read_b128 v[192:195], v200
	ds_read_b128 v[196:199], v200 offset:8192
	s_waitcnt lgkmcnt(3)
	v_mfma_f32_32x32x16_bf16 v[96:111], v[2:5], v[136:139], v[96:111]
	s_waitcnt lgkmcnt(2)
	v_mfma_f32_32x32x16_bf16 v[80:95], v[6:9], v[136:139], v[80:95]
	s_waitcnt lgkmcnt(1)
	v_mfma_f32_32x32x16_bf16 v[96:111], v[192:195], v[140:143], v[96:111]
	s_waitcnt lgkmcnt(0)
	v_mfma_f32_32x32x16_bf16 v[80:95], v[196:199], v[140:143], v[80:95]
	v_add_u32_e32 v201, s44, v169
	v_add_u32_e32 v202, s44, v170
	v_add_u32_e32 v203, s44, v171
	v_add_u32_e32 v204, s44, v172
	ds_read_b64_tr_b16 v[192:193], v201 offset:16384
	ds_read_b64_tr_b16 v[194:195], v202 offset:2048
	ds_read_b64_tr_b16 v[196:197], v203 offset:16384
	ds_read_b64_tr_b16 v[198:199], v204 offset:2048
	s_nop 1
	v_mul_f32_e64 v96, v96, s20
	v_mul_f32_e64 v97, v97, s20
	v_mul_f32_e64 v98, v98, s20
	v_mul_f32_e64 v99, v99, s20
	v_mul_f32_e64 v100, v100, s20
	v_mul_f32_e64 v101, v101, s20
	v_pk_mul_f32 v[12:13], v[102:103], s[20:21] op_sel_hi:[1,0]
	v_pk_mul_f32 v[8:9], v[104:105], s[20:21] op_sel_hi:[1,0]
	v_pk_mul_f32 v[6:7], v[106:107], s[20:21] op_sel_hi:[1,0]
	v_pk_mul_f32 v[4:5], v[108:109], s[20:21] op_sel_hi:[1,0]
	v_pk_mul_f32 v[80:81], v[80:81], s[20:21] op_sel_hi:[1,0]
	v_pk_mul_f32 v[82:83], v[82:83], s[20:21] op_sel_hi:[1,0]
	v_max_f32_e32 v0, v96, v80
	v_max3_f32 v0, v0, v97, v81
	v_max3_f32 v0, v0, v98, v82
	v_pk_mul_f32 v[84:85], v[84:85], s[20:21] op_sel_hi:[1,0]
	v_max3_f32 v0, v0, v99, v83
	v_max3_f32 v0, v0, v100, v84
	v_pk_mul_f32 v[86:87], v[86:87], s[20:21] op_sel_hi:[1,0]
	v_max3_f32 v0, v0, v101, v85
	v_max3_f32 v0, v0, v12, v86
	v_pk_mul_f32 v[88:89], v[88:89], s[20:21] op_sel_hi:[1,0]
	v_max3_f32 v0, v0, v13, v87
	v_max3_f32 v0, v0, v8, v88
	v_pk_mul_f32 v[90:91], v[90:91], s[20:21] op_sel_hi:[1,0]
	v_max3_f32 v0, v0, v9, v89
	v_max3_f32 v0, v0, v6, v90
	v_pk_mul_f32 v[92:93], v[92:93], s[20:21] op_sel_hi:[1,0]
	v_max3_f32 v0, v0, v7, v91
	v_max3_f32 v0, v0, v4, v92
	v_pk_mul_f32 v[2:3], v[110:111], s[20:21] op_sel_hi:[1,0]
	v_pk_mul_f32 v[10:11], v[94:95], s[20:21] op_sel_hi:[1,0]
	v_max3_f32 v0, v0, v5, v93
	v_max3_f32 v0, v0, v2, v10
	v_max3_f32 v0, v0, v3, v11
	ds_bpermute_b32 v14, v14, v0
	s_waitcnt lgkmcnt(0)
	v_max3_f32 v14, v181, v0, v14
	v_sub_f32_e32 v0, v181, v14
	v_exp_f32_e32 v0, v0
	s_nop 0
	v_cmp_neq_f32_e32 vcc, 1.0, v0
	s_cbranch_vccz .LBB0_239
	v_pk_mul_f32 v[78:79], v[78:79], v[0:1] op_sel_hi:[1,0]
	v_pk_mul_f32 v[76:77], v[76:77], v[0:1] op_sel_hi:[1,0]
	v_pk_mul_f32 v[74:75], v[74:75], v[0:1] op_sel_hi:[1,0]
	v_pk_mul_f32 v[72:73], v[72:73], v[0:1] op_sel_hi:[1,0]
	v_pk_mul_f32 v[70:71], v[70:71], v[0:1] op_sel_hi:[1,0]
	v_pk_mul_f32 v[68:69], v[68:69], v[0:1] op_sel_hi:[1,0]
	v_pk_mul_f32 v[66:67], v[66:67], v[0:1] op_sel_hi:[1,0]
	v_pk_mul_f32 v[64:65], v[64:65], v[0:1] op_sel_hi:[1,0]
	v_pk_mul_f32 v[62:63], v[62:63], v[0:1] op_sel_hi:[1,0]
	v_pk_mul_f32 v[60:61], v[60:61], v[0:1] op_sel_hi:[1,0]
	v_pk_mul_f32 v[58:59], v[58:59], v[0:1] op_sel_hi:[1,0]
	v_pk_mul_f32 v[56:57], v[56:57], v[0:1] op_sel_hi:[1,0]
	v_pk_mul_f32 v[54:55], v[54:55], v[0:1] op_sel_hi:[1,0]
	v_pk_mul_f32 v[52:53], v[52:53], v[0:1] op_sel_hi:[1,0]
	v_pk_mul_f32 v[50:51], v[50:51], v[0:1] op_sel_hi:[1,0]
	v_pk_mul_f32 v[48:49], v[48:49], v[0:1] op_sel_hi:[1,0]
	v_pk_mul_f32 v[46:47], v[46:47], v[0:1] op_sel_hi:[1,0]
	v_pk_mul_f32 v[44:45], v[44:45], v[0:1] op_sel_hi:[1,0]
	v_pk_mul_f32 v[42:43], v[42:43], v[0:1] op_sel_hi:[1,0]
	v_pk_mul_f32 v[40:41], v[40:41], v[0:1] op_sel_hi:[1,0]
	v_pk_mul_f32 v[38:39], v[38:39], v[0:1] op_sel_hi:[1,0]
	v_pk_mul_f32 v[36:37], v[36:37], v[0:1] op_sel_hi:[1,0]
	v_pk_mul_f32 v[34:35], v[34:35], v[0:1] op_sel_hi:[1,0]
	v_pk_mul_f32 v[32:33], v[32:33], v[0:1] op_sel_hi:[1,0]
	v_pk_mul_f32 v[30:31], v[30:31], v[0:1] op_sel_hi:[1,0]
	v_pk_mul_f32 v[28:29], v[28:29], v[0:1] op_sel_hi:[1,0]
	v_pk_mul_f32 v[26:27], v[26:27], v[0:1] op_sel_hi:[1,0]
	v_pk_mul_f32 v[24:25], v[24:25], v[0:1] op_sel_hi:[1,0]
	v_pk_mul_f32 v[22:23], v[22:23], v[0:1] op_sel_hi:[1,0]
	v_pk_mul_f32 v[20:21], v[20:21], v[0:1] op_sel_hi:[1,0]
	v_pk_mul_f32 v[18:19], v[18:19], v[0:1] op_sel_hi:[1,0]
	v_pk_mul_f32 v[16:17], v[16:17], v[0:1] op_sel_hi:[1,0]
; #define LAS __attribute__((address_space(3)))
; __device__ __forceinline__ unsigned pk2(float lo, float hi) { f32x2 v = {lo, hi}; bf16x2_t b = __builtin_convertvector(v, bf16x2_t); return __builtin_bit_cast(unsigned, b); }
; #define MFMA32(a, b, c) __builtin_amdgcn_mfma_f32_32x32x16_bf16((a), (b), (c), 0, 0, 0)
; template <int KSTEPS, class Pol>
; __device__ __forceinline__ void attn_pass(LAS unsigned char* lds, const Pol& P, const bf16_t* qb, int ldq, const bf16_t* kb, int ldk, const bf16_t* vb, int ldv,
;                                           float qs, f32x16 (&O)[4], float& m, float& l) {
;     ...
;             const f32x2 nm = {-mnew, -mnew};
; #pragma unroll
;             for (int i = 0; i < 16; i += 2) { const f32x2 a = (f32x2){S0[i], S0[i + 1]} + nm, b = (f32x2){S1[i], S1[i + 1]} + nm; S0[i] = a.x; S0[i + 1] = a.y; S1[i] = b.x; S1[i + 1] = b.y; }
;         }
;         f32x2 ls2 = {0.f, 0.f};
; #pragma unroll
;         for (int s = 0; s < 4; ++s) {
;             unsigned w[4];
; #pragma unroll
;             for (int e = 0; e < 4; ++e) {
;                 const int i = 8 * (s & 1) + 2 * e;
;                 f32x2 pv;
;                 pv.x = __builtin_amdgcn_exp2f(s < 2 ? S0[i] : S1[i]); pv.y = __builtin_amdgcn_exp2f(s < 2 ? S0[i + 1] : S1[i + 1]);
;                 ls2 = ls2 + pv;
;                 w[e] = pk2(pv.x, pv.y);
;             }
;             u32x4 wv; wv.x = w[0]; wv.y = w[1]; wv.z = w[2]; wv.w = w[3];
;             pf[s] = __builtin_bit_cast(bf16x8, wv);
;         }
;         l = l * alpha + (ls2.x + ls2.y);
;         if (__any(alpha != 1.0f)) {
; #pragma unroll
;             for (int blk = 0; blk < 4; ++blk) O[blk] = O[blk] * alpha;
;         }
;     };
;     auto pv_acc = [&](int st) __attribute__((always_inline)) {
;         LAS unsigned char* Vb = lds + st * A_STAGE;
; #pragma unroll
;         for (int s = 0; s < 4; ++s) {
; #pragma unroll
;             for (int blk = 0; blk < 4; ++blk) {
;                 const s16x4 lo = __builtin_amdgcn_ds_read_tr16_b64_v4i16((LAS s16x4*)(Vb + s * 4096 + voffs[blk][0]));
;                 const s16x4 hi = __builtin_amdgcn_ds_read_tr16_b64_v4i16((LAS s16x4*)(Vb + s * 4096 + voffs[blk][1]));
;                 const bf16x8 va = __builtin_shufflevector(lo, hi, 0, 1, 2, 3, 4, 5, 6, 7);
;                 O[blk] = MFMA32(va, pf[s], O[blk]);
;             }
;         }
.LBB0_239:
	v_pk_add_f32 v[94:95], v[96:97], v[14:15] op_sel_hi:[1,0] neg_lo:[0,1] neg_hi:[0,1]
	v_pk_add_f32 v[102:103], v[82:83], v[14:15] op_sel_hi:[1,0] neg_lo:[0,1] neg_hi:[0,1]
	v_pk_add_f32 v[82:83], v[100:101], v[14:15] op_sel_hi:[1,0] neg_lo:[0,1] neg_hi:[0,1]
	v_pk_add_f32 v[100:101], v[10:11], v[14:15] op_sel_hi:[1,0] neg_lo:[0,1] neg_hi:[0,1]
	v_exp_f32_e32 v10, v94
	v_exp_f32_e32 v11, v95
	v_pk_add_f32 v[98:99], v[98:99], v[14:15] op_sel_hi:[1,0] neg_lo:[0,1] neg_hi:[0,1]
	v_pk_add_f32 v[96:97], v[80:81], v[14:15] op_sel_hi:[1,0] neg_lo:[0,1] neg_hi:[0,1]
	v_pk_add_f32 v[12:13], v[12:13], v[14:15] op_sel_hi:[1,0] neg_lo:[0,1] neg_hi:[0,1]
	v_pk_add_f32 v[94:95], v[10:11], 0 op_sel_hi:[1,0]
	v_cvt_pk_bf16_f32 v80, v10, v11
	v_exp_f32_e32 v10, v98
	v_exp_f32_e32 v11, v99
	v_pk_add_f32 v[8:9], v[8:9], v[14:15] op_sel_hi:[1,0] neg_lo:[0,1] neg_hi:[0,1]
	v_pk_add_f32 v[6:7], v[6:7], v[14:15] op_sel_hi:[1,0] neg_lo:[0,1] neg_hi:[0,1]
	v_exp_f32_e32 v8, v8
	v_pk_add_f32 v[94:95], v[10:11], v[94:95]
	v_cvt_pk_bf16_f32 v81, v10, v11
	v_exp_f32_e32 v10, v82
	v_exp_f32_e32 v11, v83
	v_exp_f32_e32 v9, v9
	v_pk_add_f32 v[4:5], v[4:5], v[14:15] op_sel_hi:[1,0] neg_lo:[0,1] neg_hi:[0,1]
	v_exp_f32_e32 v6, v6
	v_pk_add_f32 v[94:95], v[10:11], v[94:95]
	v_cvt_pk_bf16_f32 v82, v10, v11
	v_exp_f32_e32 v10, v12
	v_exp_f32_e32 v11, v13
	v_exp_f32_e32 v7, v7
	v_pk_add_f32 v[2:3], v[2:3], v[14:15] op_sel_hi:[1,0] neg_lo:[0,1] neg_hi:[0,1]
	v_exp_f32_e32 v4, v4
	v_exp_f32_e32 v5, v5
	v_pk_add_f32 v[12:13], v[10:11], v[94:95]
	v_exp_f32_e32 v2, v2
	v_exp_f32_e32 v3, v3
	v_pk_add_f32 v[12:13], v[8:9], v[12:13]
	v_cvt_pk_bf16_f32 v83, v10, v11
	v_cvt_pk_bf16_f32 v10, v8, v9
	v_pk_add_f32 v[8:9], v[6:7], v[12:13]
	v_cvt_pk_bf16_f32 v11, v6, v7
	v_pk_add_f32 v[6:7], v[4:5], v[8:9]
	v_cvt_pk_bf16_f32 v12, v4, v5
	v_pk_add_f32 v[4:5], v[2:3], v[6:7]
	v_cvt_pk_bf16_f32 v13, v2, v3
	v_exp_f32_e32 v2, v96
	v_exp_f32_e32 v3, v97
	v_pk_add_f32 v[84:85], v[84:85], v[14:15] op_sel_hi:[1,0] neg_lo:[0,1] neg_hi:[0,1]
	v_pk_add_f32 v[86:87], v[86:87], v[14:15] op_sel_hi:[1,0] neg_lo:[0,1] neg_hi:[0,1]
	v_pk_add_f32 v[88:89], v[88:89], v[14:15] op_sel_hi:[1,0] neg_lo:[0,1] neg_hi:[0,1]
	v_pk_add_f32 v[4:5], v[2:3], v[4:5]
	v_cvt_pk_bf16_f32 v6, v2, v3
	v_exp_f32_e32 v2, v102
	v_exp_f32_e32 v3, v103
	v_pk_add_f32 v[90:91], v[90:91], v[14:15] op_sel_hi:[1,0] neg_lo:[0,1] neg_hi:[0,1]
	v_pk_add_f32 v[92:93], v[92:93], v[14:15] op_sel_hi:[1,0] neg_lo:[0,1] neg_hi:[0,1]
	v_add_u32_e32 v94, s44, v176
	v_pk_add_f32 v[4:5], v[2:3], v[4:5]
	v_cvt_pk_bf16_f32 v7, v2, v3
	v_exp_f32_e32 v2, v84
	v_exp_f32_e32 v3, v85
	v_exp_f32_e32 v84, v90
	v_exp_f32_e32 v85, v91
	v_add_u32_e32 v90, s44, v172
	v_pk_add_f32 v[4:5], v[2:3], v[4:5]
	v_cvt_pk_bf16_f32 v8, v2, v3
	v_exp_f32_e32 v2, v86
	v_exp_f32_e32 v3, v87
	v_add_u32_e32 v91, s44, v173
	v_pk_add_f32 v[4:5], v[2:3], v[4:5]
	v_cvt_pk_bf16_f32 v9, v2, v3
	v_exp_f32_e32 v2, v88
	v_exp_f32_e32 v3, v89
	v_add_u32_e32 v88, s44, v170
	v_add_u32_e32 v89, s44, v171
	v_pk_add_f32 v[4:5], v[2:3], v[4:5]
	v_cvt_pk_bf16_f32 v2, v2, v3
	v_pk_add_f32 v[4:5], v[84:85], v[4:5]
	v_cvt_pk_bf16_f32 v3, v84, v85
	v_exp_f32_e32 v84, v92
	v_exp_f32_e32 v85, v93
	v_add_u32_e32 v92, s44, v174
	v_add_u32_e32 v93, s44, v175
	v_pk_add_f32 v[86:87], v[84:85], v[4:5]
	v_cvt_pk_bf16_f32 v4, v84, v85
	v_exp_f32_e32 v84, v100
	v_exp_f32_e32 v85, v101
	s_nop 0
	v_pk_add_f32 v[86:87], v[84:85], v[86:87]
	s_nop 0
	v_add_f32_e32 v15, v86, v87
	v_fmac_f32_e32 v15, v180, v0
	v_add_u32_e32 v0, s44, v169
	v_cvt_pk_bf16_f32 v5, v84, v85
	s_waitcnt lgkmcnt(2)
	v_mfma_f32_32x32x16_bf16 v[64:79], v[192:195], v[80:83], v[64:79]
	ds_read_b64_tr_b16 v[192:193], v91 offset:16384
	ds_read_b64_tr_b16 v[194:195], v92 offset:2048
	v_mov_b32_e32 v180, v15
	s_waitcnt lgkmcnt(2)
	v_mfma_f32_32x32x16_bf16 v[48:63], v[196:199], v[80:83], v[48:63]
	ds_read_b64_tr_b16 v[196:197], v93 offset:16384
	ds_read_b64_tr_b16 v[198:199], v94 offset:2048
	s_waitcnt lgkmcnt(2)
	v_mfma_f32_32x32x16_bf16 v[32:47], v[192:195], v[80:83], v[32:47]
	ds_read_b64_tr_b16 v[192:193], v0 offset:20480
	ds_read_b64_tr_b16 v[194:195], v88 offset:6144
	s_waitcnt lgkmcnt(2)
	v_mfma_f32_32x32x16_bf16 v[16:31], v[196:199], v[80:83], v[16:31]
	ds_read_b64_tr_b16 v[196:197], v89 offset:20480
	ds_read_b64_tr_b16 v[198:199], v90 offset:6144
	s_waitcnt lgkmcnt(2)
	v_mfma_f32_32x32x16_bf16 v[64:79], v[192:195], v[10:13], v[64:79]
	ds_read_b64_tr_b16 v[192:193], v91 offset:20480
	ds_read_b64_tr_b16 v[194:195], v92 offset:6144
	s_waitcnt lgkmcnt(2)
	v_mfma_f32_32x32x16_bf16 v[48:63], v[196:199], v[10:13], v[48:63]
	ds_read_b64_tr_b16 v[196:197], v93 offset:20480
	ds_read_b64_tr_b16 v[198:199], v94 offset:6144
	s_waitcnt lgkmcnt(2)
	v_mfma_f32_32x32x16_bf16 v[32:47], v[192:195], v[10:13], v[32:47]
	ds_read_b64_tr_b16 v[192:193], v0 offset:24576
	ds_read_b64_tr_b16 v[194:195], v88 offset:10240
	s_waitcnt lgkmcnt(2)
	v_mfma_f32_32x32x16_bf16 v[16:31], v[196:199], v[10:13], v[16:31]
	ds_read_b64_tr_b16 v[196:197], v89 offset:24576
	ds_read_b64_tr_b16 v[198:199], v90 offset:10240
	s_waitcnt lgkmcnt(2)
	v_mfma_f32_32x32x16_bf16 v[64:79], v[192:195], v[6:9], v[64:79]
	ds_read_b64_tr_b16 v[192:193], v91 offset:24576
	ds_read_b64_tr_b16 v[194:195], v92 offset:10240
	s_waitcnt lgkmcnt(2)
	v_mfma_f32_32x32x16_bf16 v[48:63], v[196:199], v[6:9], v[48:63]
	ds_read_b64_tr_b16 v[196:197], v93 offset:24576
	ds_read_b64_tr_b16 v[198:199], v94 offset:10240
	s_waitcnt lgkmcnt(2)
	v_mfma_f32_32x32x16_bf16 v[32:47], v[192:195], v[6:9], v[32:47]
	ds_read_b64_tr_b16 v[192:193], v0 offset:28672
	ds_read_b64_tr_b16 v[194:195], v88 offset:14336
	s_waitcnt lgkmcnt(2)
	v_mfma_f32_32x32x16_bf16 v[16:31], v[196:199], v[6:9], v[16:31]
	ds_read_b64_tr_b16 v[196:197], v89 offset:28672
	ds_read_b64_tr_b16 v[198:199], v90 offset:14336
	s_waitcnt lgkmcnt(2)
	v_mfma_f32_32x32x16_bf16 v[64:79], v[192:195], v[2:5], v[64:79]
	ds_read_b64_tr_b16 v[192:193], v91 offset:28672
	ds_read_b64_tr_b16 v[194:195], v92 offset:14336
	s_waitcnt lgkmcnt(2)
	v_mfma_f32_32x32x16_bf16 v[48:63], v[196:199], v[2:5], v[48:63]
	ds_read_b64_tr_b16 v[196:197], v93 offset:28672
	ds_read_b64_tr_b16 v[198:199], v94 offset:14336
	s_waitcnt lgkmcnt(2)
	v_mfma_f32_32x32x16_bf16 v[32:47], v[192:195], v[2:5], v[32:47]
	s_waitcnt lgkmcnt(0)
	v_mfma_f32_32x32x16_bf16 v[16:31], v[196:199], v[2:5], v[16:31]
	s_cmp_gt_u32 s71, 4
	s_cbranch_scc0 .LBB0_241
	s_branch .LBB0_246

; #define LAS __attribute__((address_space(3)))
; template <int KSTEPS, class Pol>
; __device__ __forceinline__ void attn_pass(LAS unsigned char* lds, const Pol& P, const bf16_t* qb, int ldq, const bf16_t* kb, int ldk, const bf16_t* vb, int ldv,
;                                           float qs, f32x16 (&O)[4], float& m, float& l) {
;     ...
;         for (int ks = 0; ks < KSTEPS; ++ks) {
;             const int so = ((2 * ks) ^ kx) << 4;
;             const bf16x8 a0 = *(const LAS bf16x8*)(Kb + so);
;             const bf16x8 a1 = *(const LAS bf16x8*)(Kb + 32 * KROWB + so);
;     __device__ __forceinline__ float bias(int qi, int half, int t, int jc) const {
;         const int j = jc + 4 * half;
;         const int r = R + (qi >> 6), c = qi & 63, kr = kr_lo + t, c0 = min(max(c - 8, 0), 48);
;         const bool ok = (j >= c0) && (j < c0 + 16);
;         const int idx = min(max((kr - r + 7) * 31 + (j - c + 15), 0), 15 * 31 - 1);
;         const float bv = rpb[idx];
;         return ok ? bv : -__builtin_inff();
;     }
;     __device__ __forceinline__ void fill(f32x16& S0, f32x16& S1, int qi, int half, int t, int) const {
; #pragma unroll
;         for (int i = 0; i < 16; ++i) { const int jc = 8 * (i >> 2) + (i & 3); S0[i] = bias(qi, half, t, jc); S1[i] = bias(qi, half, t, 32 + jc); }
.LBB0_463:
	s_add_i32 s51, s42, s49
	s_cmp_lt_u32 s51, s46
	s_cselect_b64 vcc, -1, 0
	s_cmp_gt_u32 s51, s47
	s_cselect_b64 s[52:53], -1, 0
	s_or_b64 s[52:53], vcc, s[52:53]
	s_and_b64 vcc, exec, s[52:53]
	s_cbranch_vccnz .LBB0_467
	v_subrev_u32_e32 v2, 59, v172
	v_subrev_u32_e32 v3, 27, v172
	v_subrev_u32_e32 v4, 58, v172
	v_subrev_u32_e32 v5, 26, v172
	v_subrev_u32_e32 v6, 57, v172
	v_subrev_u32_e32 v7, 25, v172
	v_subrev_u32_e32 v8, 56, v172
	v_subrev_u32_e32 v9, 24, v172
	v_med3_i32 v2, v2, 0, v239
	s_add_i32 vcc_lo, 0, 0x18000
	v_med3_i32 v3, v3, 0, v239
	v_med3_i32 v4, v4, 0, v239
	v_med3_i32 v5, v5, 0, v239
	v_med3_i32 v6, v6, 0, v239
	v_med3_i32 v7, v7, 0, v239
	v_med3_i32 v8, v8, 0, v239
	v_med3_i32 v9, v9, 0, v239
	v_readlane_b32 s52, v250, 1
	v_lshl_add_u32 v2, v2, 2, vcc_lo
	v_lshl_add_u32 v3, v3, 2, vcc_lo
	v_lshl_add_u32 v4, v4, 2, vcc_lo
	v_lshl_add_u32 v5, v5, 2, vcc_lo
	v_lshl_add_u32 v6, v6, 2, vcc_lo
	v_lshl_add_u32 v7, v7, 2, vcc_lo
	v_lshl_add_u32 v8, v8, 2, vcc_lo
	v_lshl_add_u32 v9, v9, 2, vcc_lo
	v_readlane_b32 s53, v250, 2
	ds_read_b32 v2, v2
	ds_read_b32 v3, v3
	ds_read_b32 v4, v4
	ds_read_b32 v5, v5
	ds_read_b32 v6, v6
	ds_read_b32 v7, v7
	ds_read_b32 v8, v8
	ds_read_b32 v9, v9
	s_waitcnt lgkmcnt(6)
	v_cndmask_b32_e64 v80, v238, v3, s[52:53]
	v_readlane_b32 s52, v250, 3
	v_readlane_b32 s53, v250, 4
	v_cndmask_b32_e64 v96, v2, v238, s[36:37]
	v_subrev_u32_e32 v2, 51, v172
	s_waitcnt lgkmcnt(5)
	v_cndmask_b32_e64 v97, v4, v238, s[52:53]
	v_readlane_b32 s52, v250, 5
	v_readlane_b32 s53, v250, 6
	v_subrev_u32_e32 v3, 19, v172
	v_subrev_u32_e32 v4, 50, v172
	s_waitcnt lgkmcnt(4)
	v_cndmask_b32_e64 v81, v238, v5, s[52:53]
	v_readlane_b32 s52, v250, 7
	v_readlane_b32 s53, v250, 8
	v_subrev_u32_e32 v5, 18, v172
	v_med3_i32 v2, v2, 0, v239
	s_waitcnt lgkmcnt(3)
	v_cndmask_b32_e64 v98, v6, v238, s[52:53]
	v_readlane_b32 s52, v250, 9
	v_readlane_b32 s53, v250, 10
	v_subrev_u32_e32 v6, 49, v172
	v_med3_i32 v3, v3, 0, v239
	s_waitcnt lgkmcnt(2)
	v_cndmask_b32_e64 v82, v238, v7, s[52:53]
	v_readlane_b32 s52, v250, 11
	v_readlane_b32 s53, v250, 12
	v_subrev_u32_e32 v7, 17, v172
	v_med3_i32 v4, v4, 0, v239
	s_waitcnt lgkmcnt(1)
	v_cndmask_b32_e64 v99, v8, v238, s[52:53]
	v_readlane_b32 s52, v250, 13
	v_readlane_b32 s53, v250, 14
	v_subrev_u32_e32 v8, 48, v172
	v_med3_i32 v5, v5, 0, v239
	s_waitcnt lgkmcnt(0)
	v_cndmask_b32_e64 v83, v238, v9, s[52:53]
	v_add_u32_e32 v9, -16, v172
	v_med3_i32 v6, v6, 0, v239
	v_med3_i32 v7, v7, 0, v239
	v_med3_i32 v8, v8, 0, v239
	v_med3_i32 v9, v9, 0, v239
	v_lshl_add_u32 v2, v2, 2, vcc_lo
	v_lshl_add_u32 v3, v3, 2, vcc_lo
	v_lshl_add_u32 v4, v4, 2, vcc_lo
	v_lshl_add_u32 v5, v5, 2, vcc_lo
	v_lshl_add_u32 v6, v6, 2, vcc_lo
	v_lshl_add_u32 v7, v7, 2, vcc_lo
	v_lshl_add_u32 v8, v8, 2, vcc_lo
	v_lshl_add_u32 v9, v9, 2, vcc_lo
	ds_read_b32 v2, v2
	ds_read_b32 v3, v3
	ds_read_b32 v4, v4
	ds_read_b32 v5, v5
	ds_read_b32 v6, v6
	ds_read_b32 v7, v7
	ds_read_b32 v8, v8
	ds_read_b32 v9, v9
	v_readlane_b32 s52, v250, 15
	v_readlane_b32 s53, v250, 16
	s_waitcnt lgkmcnt(6)
	v_cndmask_b32_e64 v84, v238, v3, s[54:55]
	s_waitcnt lgkmcnt(5)
	v_cndmask_b32_e64 v101, v4, v238, s[56:57]
	v_cndmask_b32_e64 v100, v2, v238, s[52:53]
	s_waitcnt lgkmcnt(4)
	v_cndmask_b32_e64 v85, v238, v5, s[58:59]
	s_waitcnt lgkmcnt(3)
	v_cndmask_b32_e64 v102, v6, v238, s[60:61]
	v_subrev_u32_e32 v2, 43, v172
	v_add_u32_e32 v3, -11, v172
	v_subrev_u32_e32 v4, 42, v172
	v_add_u32_e32 v5, -10, v172
	v_subrev_u32_e32 v6, 41, v172
	s_waitcnt lgkmcnt(2)
	v_cndmask_b32_e64 v86, v238, v7, s[62:63]
	s_waitcnt lgkmcnt(1)
	v_cndmask_b32_e64 v103, v8, v238, s[64:65]
	s_waitcnt lgkmcnt(0)
	v_cndmask_b32_e64 v87, v238, v9, s[40:41]
	v_med3_i32 v2, v2, 0, v239
	v_med3_i32 v3, v3, 0, v239
	v_med3_i32 v4, v4, 0, v239
	v_med3_i32 v5, v5, 0, v239
	v_med3_i32 v6, v6, 0, v239
	v_add_u32_e32 v7, -9, v172
	v_subrev_u32_e32 v8, 40, v172
	v_add_u32_e32 v9, -8, v172
	v_lshl_add_u32 v2, v2, 2, vcc_lo
	v_lshl_add_u32 v3, v3, 2, vcc_lo
	v_lshl_add_u32 v4, v4, 2, vcc_lo
	v_lshl_add_u32 v5, v5, 2, vcc_lo
	v_lshl_add_u32 v6, v6, 2, vcc_lo
	v_med3_i32 v7, v7, 0, v239
	v_med3_i32 v8, v8, 0, v239
	v_med3_i32 v9, v9, 0, v239
	v_lshl_add_u32 v7, v7, 2, vcc_lo
	v_lshl_add_u32 v8, v8, 2, vcc_lo
	v_lshl_add_u32 v9, v9, 2, vcc_lo
	ds_read_b32 v2, v2
	ds_read_b32 v3, v3
	ds_read_b32 v4, v4
	ds_read_b32 v10, v5
	ds_read_b32 v5, v6
	ds_read_b32 v11, v7
	ds_read_b32 v6, v8
	ds_read_b32 v12, v9
	s_waitcnt lgkmcnt(7)
	v_cndmask_b32_e64 v104, v238, v2, s[68:69]
	v_subrev_u32_e32 v2, 35, v172
	v_med3_i32 v2, v2, 0, v239
	s_waitcnt lgkmcnt(1)
	v_cndmask_b32_e64 v107, v238, v6, s[80:81]
	v_lshl_add_u32 v6, v2, 2, vcc_lo
	v_add_u32_e32 v2, -3, v172
	v_med3_i32 v2, v2, 0, v239
	v_lshl_add_u32 v7, v2, 2, vcc_lo
	v_subrev_u32_e32 v2, 34, v172
	v_med3_i32 v2, v2, 0, v239
	v_lshl_add_u32 v8, v2, 2, vcc_lo
	v_add_u32_e32 v2, -2, v172
	v_med3_i32 v2, v2, 0, v239
	v_lshl_add_u32 v9, v2, 2, vcc_lo
	v_subrev_u32_e32 v2, 33, v172
	v_med3_i32 v2, v2, 0, v239
	v_lshl_add_u32 v13, v2, 2, vcc_lo
	v_add_u32_e32 v2, -1, v172
	s_lshl_b32 s51, s50, 15
	v_med3_i32 v2, v2, 0, v239
	s_add_i32 s51, s51, 0
	v_lshl_add_u32 v14, v2, 2, vcc_lo
	v_subrev_u32_e32 v2, 32, v172
	v_add_u32_e32 v0, s51, v145
	v_med3_i32 v2, v2, 0, v239
	v_lshl_add_u32 v15, v2, 2, vcc_lo
	v_med3_i32 v2, v172, 0, v239
	v_add_u32_e32 v90, v0, v156
	v_cndmask_b32_e64 v88, v238, v3, s[70:71]
	v_cndmask_b32_e64 v105, v238, v4, s[72:73]
	v_cndmask_b32_e64 v106, v238, v5, s[76:77]
	v_lshl_add_u32 v89, v2, 2, vcc_lo
	ds_read_b128 v[2:5], v90
	ds_read_b32 v6, v6
	ds_read_b32 v92, v7
	ds_read_b32 v7, v8
	ds_read_b32 v93, v9
	ds_read_b32 v8, v13
	ds_read_b32 v13, v14
	ds_read_b32 v9, v15
	ds_read_b32 v14, v89
	s_waitcnt lgkmcnt(7)
; #define LAS __attribute__((address_space(3)))
; template <int KSTEPS, class Pol>
; __device__ __forceinline__ void attn_pass(LAS unsigned char* lds, const Pol& P, const bf16_t* qb, int ldq, const bf16_t* kb, int ldk, const bf16_t* vb, int ldv,
;                                           float qs, f32x16 (&O)[4], float& m, float& l) {
;     ...
;         for (int ks = 0; ks < KSTEPS; ++ks) {
;             const int so = ((2 * ks) ^ kx) << 4;
;             const bf16x8 a0 = *(const LAS bf16x8*)(Kb + so);
;             const bf16x8 a1 = *(const LAS bf16x8*)(Kb + 32 * KROWB + so);
;             S0 = MFMA32(a0, qf[ks], S0);
;             S1 = MFMA32(a1, qf[ks], S1);
;         }
;         S0 = S0 * qs; S1 = S1 * qs;
;         float mx = fmaxf(S0[0], S1[0]);
; #pragma unroll
;         for (int i = 1; i < 16; ++i) mx = fmaxf(fmaxf(mx, S0[i]), S1[i]);
;         mx = fmaxf(mx, __shfl_xor(mx, 32));
;         const float mnew = fmaxf(m, mx);
;         const float alpha = __builtin_amdgcn_exp2f(m - mnew);
;         m = mnew;
;         {
;             const f32x2 nm = {-mnew, -mnew};
; #pragma unroll
;             for (int i = 0; i < 16; i += 2) { const f32x2 a = (f32x2){S0[i], S0[i + 1]} + nm, b = (f32x2){S1[i], S1[i + 1]} + nm; S0[i] = a.x; S0[i + 1] = a.y; S1[i] = b.x; S1[i + 1] = b.y; }
;         }
;         f32x2 ls2 = {0.f, 0.f};
; #pragma unroll
;         for (int s = 0; s < 4; ++s) {
;             unsigned w[4];
; #pragma unroll
;             for (int e = 0; e < 4; ++e) {
;                 const int i = 8 * (s & 1) + 2 * e;
;                 f32x2 pv;
;                 pv.x = __builtin_amdgcn_exp2f(s < 2 ? S0[i] : S1[i]); pv.y = __builtin_amdgcn_exp2f(s < 2 ? S0[i + 1] : S1[i + 1]);
;                 ls2 = ls2 + pv;
;                 w[e] = pk2(pv.x, pv.y);
;             }
;             u32x4 wv; wv.x = w[0]; wv.y = w[1]; wv.z = w[2]; wv.w = w[3];
;             pf[s] = __builtin_bit_cast(bf16x8, wv);
;         }
;         l = l * alpha + (ls2.x + ls2.y);
;         if (__any(alpha != 1.0f)) {
; #pragma unroll
;             for (int blk = 0; blk < 4; ++blk) O[blk] = O[blk] * alpha;
;         }
;     ...
;     auto pv_acc = [&](int st) __attribute__((always_inline)) {
;         LAS unsigned char* Vb = lds + st * A_STAGE;
; #pragma unroll
;         for (int s = 0; s < 4; ++s) {
; #pragma unroll
;             for (int blk = 0; blk < 4; ++blk) {
	v_cndmask_b32_e64 v108, v238, v6, s[84:85]
	s_waitcnt lgkmcnt(5)
	v_cndmask_b32_e64 v109, v238, v7, s[88:89]
	s_waitcnt lgkmcnt(3)
	v_cndmask_b32_e64 v110, v238, v8, s[92:93]
	s_waitcnt lgkmcnt(1)
	v_cndmask_b32_e64 v111, v238, v9, s[96:97]
	ds_read_b128 v[6:9], v90 offset:8192
	v_cndmask_b32_e64 v89, v238, v10, s[74:75]
	v_cndmask_b32_e64 v90, v238, v11, s[78:79]
	v_cndmask_b32_e64 v91, v238, v12, s[82:83]
	v_cndmask_b32_e64 v92, v238, v92, s[86:87]
	v_cndmask_b32_e64 v93, v238, v93, s[90:91]
	v_cndmask_b32_e64 v94, v238, v13, s[94:95]
	s_waitcnt lgkmcnt(1)
	v_cndmask_b32_e64 v95, v238, v14, s[2:3]
	v_mfma_f32_32x32x16_bf16 v[96:111], v[2:5], v[112:115], v[96:111]
	v_and_b32_e32 v15, 64, v234
	v_xor_b32_e32 v14, 32, v234
	v_add_u32_e32 v15, 64, v15
	v_cmp_lt_i32_e32 vcc, v14, v15
	s_nop 1
	v_cndmask_b32_e32 v14, v234, v14, vcc
	s_waitcnt lgkmcnt(0)
	v_mfma_f32_32x32x16_bf16 v[80:95], v[6:9], v[112:115], v[80:95]
	v_add_u32_e32 v6, v0, v157
	ds_read_b128 v[2:5], v6
	ds_read_b128 v[6:9], v6 offset:8192
	v_add_u32_e32 v200, v0, v158
	ds_read_b128 v[192:195], v200
	ds_read_b128 v[196:199], v200 offset:8192
	v_lshlrev_b32_e32 v14, 2, v14
	s_waitcnt lgkmcnt(3)
	v_mfma_f32_32x32x16_bf16 v[96:111], v[2:5], v[116:119], v[96:111]
	s_waitcnt lgkmcnt(2)
	v_mfma_f32_32x32x16_bf16 v[80:95], v[6:9], v[116:119], v[80:95]
	v_add_u32_e32 v6, v0, v159
	ds_read_b128 v[2:5], v6
	ds_read_b128 v[6:9], v6 offset:8192
	s_waitcnt lgkmcnt(3)
	v_mfma_f32_32x32x16_bf16 v[96:111], v[192:195], v[120:123], v[96:111]
	s_waitcnt lgkmcnt(2)
	v_mfma_f32_32x32x16_bf16 v[80:95], v[196:199], v[120:123], v[80:95]
	v_add_u32_e32 v200, v0, v160
	ds_read_b128 v[192:195], v200
	ds_read_b128 v[196:199], v200 offset:8192
	s_waitcnt lgkmcnt(3)
	v_mfma_f32_32x32x16_bf16 v[96:111], v[2:5], v[124:127], v[96:111]
	s_waitcnt lgkmcnt(2)
	v_mfma_f32_32x32x16_bf16 v[80:95], v[6:9], v[124:127], v[80:95]
	v_add_u32_e32 v6, v0, v161
	ds_read_b128 v[2:5], v6
	ds_read_b128 v[6:9], v6 offset:8192
	s_waitcnt lgkmcnt(3)
	v_mfma_f32_32x32x16_bf16 v[96:111], v[192:195], v[128:131], v[96:111]
	s_waitcnt lgkmcnt(2)
	v_mfma_f32_32x32x16_bf16 v[80:95], v[196:199], v[128:131], v[80:95]
	v_add_u32_e32 v200, v0, v162
	ds_read_b128 v[192:195], v200
	ds_read_b128 v[196:199], v200 offset:8192
	s_waitcnt lgkmcnt(3)
	v_mfma_f32_32x32x16_bf16 v[96:111], v[2:5], v[132:135], v[96:111]
	s_waitcnt lgkmcnt(2)
	v_mfma_f32_32x32x16_bf16 v[80:95], v[6:9], v[132:135], v[80:95]
	v_add_u32_e32 v201, v0, v163
	ds_read_b128 v[2:5], v201
	ds_read_b128 v[6:9], v201 offset:8192
	s_waitcnt lgkmcnt(3)
	v_mfma_f32_32x32x16_bf16 v[96:111], v[192:195], v[136:139], v[96:111]
	s_waitcnt lgkmcnt(2)
	v_mfma_f32_32x32x16_bf16 v[80:95], v[196:199], v[136:139], v[80:95]
	s_waitcnt lgkmcnt(1)
	v_mfma_f32_32x32x16_bf16 v[96:111], v[2:5], v[140:143], v[96:111]
	s_waitcnt lgkmcnt(0)
	v_mfma_f32_32x32x16_bf16 v[80:95], v[6:9], v[140:143], v[80:95]
	v_add_u32_e32 v201, s51, v164
	v_add_u32_e32 v202, s51, v165
	v_add_u32_e32 v203, s51, v166
	v_add_u32_e32 v204, s51, v167
	ds_read_b64_tr_b16 v[192:193], v201 offset:16384
	ds_read_b64_tr_b16 v[194:195], v202 offset:2048
	ds_read_b64_tr_b16 v[196:197], v203 offset:16384
	ds_read_b64_tr_b16 v[198:199], v204 offset:2048
	s_nop 1
	v_mul_f32_e64 v96, v96, s20
	v_mul_f32_e64 v97, v97, s20
	v_mul_f32_e64 v98, v98, s20
	v_mul_f32_e64 v99, v99, s20
	v_mul_f32_e64 v100, v100, s20
	v_mul_f32_e64 v101, v101, s20
	v_pk_mul_f32 v[102:103], v[102:103], s[20:21] op_sel_hi:[1,0]
	v_pk_mul_f32 v[10:11], v[104:105], s[20:21] op_sel_hi:[1,0]
	v_pk_mul_f32 v[6:7], v[106:107], s[20:21] op_sel_hi:[1,0]
	v_pk_mul_f32 v[4:5], v[108:109], s[20:21] op_sel_hi:[1,0]
	v_pk_mul_f32 v[80:81], v[80:81], s[20:21] op_sel_hi:[1,0]
	v_pk_mul_f32 v[82:83], v[82:83], s[20:21] op_sel_hi:[1,0]
	v_max_f32_e32 v0, v96, v80
	v_max3_f32 v0, v0, v97, v81
	v_max3_f32 v0, v0, v98, v82
	v_pk_mul_f32 v[84:85], v[84:85], s[20:21] op_sel_hi:[1,0]
	v_max3_f32 v0, v0, v99, v83
	v_max3_f32 v0, v0, v100, v84
	v_pk_mul_f32 v[86:87], v[86:87], s[20:21] op_sel_hi:[1,0]
	v_max3_f32 v0, v0, v101, v85
	v_max3_f32 v0, v0, v102, v86
	v_pk_mul_f32 v[88:89], v[88:89], s[20:21] op_sel_hi:[1,0]
	v_max3_f32 v0, v0, v103, v87
	v_max3_f32 v0, v0, v10, v88
	v_pk_mul_f32 v[90:91], v[90:91], s[20:21] op_sel_hi:[1,0]
	v_max3_f32 v0, v0, v11, v89
	v_max3_f32 v0, v0, v6, v90
	v_pk_mul_f32 v[12:13], v[92:93], s[20:21] op_sel_hi:[1,0]
	v_max3_f32 v0, v0, v7, v91
	v_max3_f32 v0, v0, v4, v12
	v_pk_mul_f32 v[2:3], v[110:111], s[20:21] op_sel_hi:[1,0]
	v_pk_mul_f32 v[8:9], v[94:95], s[20:21] op_sel_hi:[1,0]
	v_max3_f32 v0, v0, v5, v13
	v_max3_f32 v0, v0, v2, v8
	v_max3_f32 v0, v0, v3, v9
	ds_bpermute_b32 v14, v14, v0
	s_waitcnt lgkmcnt(0)
	v_max3_f32 v0, v175, v0, v14
	v_sub_f32_e32 v14, v175, v0
	v_exp_f32_e32 v14, v14
	s_nop 0
	v_cmp_neq_f32_e32 vcc, 1.0, v14
	s_cbranch_vccz .LBB0_466
	v_pk_mul_f32 v[78:79], v[78:79], v[14:15] op_sel_hi:[1,0]
	v_pk_mul_f32 v[76:77], v[76:77], v[14:15] op_sel_hi:[1,0]
	v_pk_mul_f32 v[74:75], v[74:75], v[14:15] op_sel_hi:[1,0]
	v_pk_mul_f32 v[72:73], v[72:73], v[14:15] op_sel_hi:[1,0]
	v_pk_mul_f32 v[70:71], v[70:71], v[14:15] op_sel_hi:[1,0]
	v_pk_mul_f32 v[68:69], v[68:69], v[14:15] op_sel_hi:[1,0]
	v_pk_mul_f32 v[66:67], v[66:67], v[14:15] op_sel_hi:[1,0]
	v_pk_mul_f32 v[64:65], v[64:65], v[14:15] op_sel_hi:[1,0]
	v_pk_mul_f32 v[62:63], v[62:63], v[14:15] op_sel_hi:[1,0]
	v_pk_mul_f32 v[60:61], v[60:61], v[14:15] op_sel_hi:[1,0]
	v_pk_mul_f32 v[58:59], v[58:59], v[14:15] op_sel_hi:[1,0]
	v_pk_mul_f32 v[56:57], v[56:57], v[14:15] op_sel_hi:[1,0]
	v_pk_mul_f32 v[54:55], v[54:55], v[14:15] op_sel_hi:[1,0]
	v_pk_mul_f32 v[52:53], v[52:53], v[14:15] op_sel_hi:[1,0]
	v_pk_mul_f32 v[50:51], v[50:51], v[14:15] op_sel_hi:[1,0]
	v_pk_mul_f32 v[48:49], v[48:49], v[14:15] op_sel_hi:[1,0]
	v_pk_mul_f32 v[46:47], v[46:47], v[14:15] op_sel_hi:[1,0]
	v_pk_mul_f32 v[44:45], v[44:45], v[14:15] op_sel_hi:[1,0]
	v_pk_mul_f32 v[42:43], v[42:43], v[14:15] op_sel_hi:[1,0]
	v_pk_mul_f32 v[40:41], v[40:41], v[14:15] op_sel_hi:[1,0]
	v_pk_mul_f32 v[38:39], v[38:39], v[14:15] op_sel_hi:[1,0]
	v_pk_mul_f32 v[36:37], v[36:37], v[14:15] op_sel_hi:[1,0]
	v_pk_mul_f32 v[34:35], v[34:35], v[14:15] op_sel_hi:[1,0]
	v_pk_mul_f32 v[32:33], v[32:33], v[14:15] op_sel_hi:[1,0]
	v_pk_mul_f32 v[30:31], v[30:31], v[14:15] op_sel_hi:[1,0]
	v_pk_mul_f32 v[28:29], v[28:29], v[14:15] op_sel_hi:[1,0]
	v_pk_mul_f32 v[26:27], v[26:27], v[14:15] op_sel_hi:[1,0]
	v_pk_mul_f32 v[24:25], v[24:25], v[14:15] op_sel_hi:[1,0]
	v_pk_mul_f32 v[22:23], v[22:23], v[14:15] op_sel_hi:[1,0]
	v_pk_mul_f32 v[20:21], v[20:21], v[14:15] op_sel_hi:[1,0]
	v_pk_mul_f32 v[18:19], v[18:19], v[14:15] op_sel_hi:[1,0]
	v_pk_mul_f32 v[16:17], v[16:17], v[14:15] op_sel_hi:[1,0]
; #define LAS __attribute__((address_space(3)))
; __device__ __forceinline__ unsigned pk2(float lo, float hi) { f32x2 v = {lo, hi}; bf16x2_t b = __builtin_convertvector(v, bf16x2_t); return __builtin_bit_cast(unsigned, b); }
; #define MFMA32(a, b, c) __builtin_amdgcn_mfma_f32_32x32x16_bf16((a), (b), (c), 0, 0, 0)
; template <int KSTEPS, class Pol>
; __device__ __forceinline__ void attn_pass(LAS unsigned char* lds, const Pol& P, const bf16_t* qb, int ldq, const bf16_t* kb, int ldk, const bf16_t* vb, int ldv,
;                                           float qs, f32x16 (&O)[4], float& m, float& l) {
;     ...
;             const f32x2 nm = {-mnew, -mnew};
; #pragma unroll
;             for (int i = 0; i < 16; i += 2) { const f32x2 a = (f32x2){S0[i], S0[i + 1]} + nm, b = (f32x2){S1[i], S1[i + 1]} + nm; S0[i] = a.x; S0[i + 1] = a.y; S1[i] = b.x; S1[i + 1] = b.y; }
;         }
;         f32x2 ls2 = {0.f, 0.f};
; #pragma unroll
;         for (int s = 0; s < 4; ++s) {
;             unsigned w[4];
; #pragma unroll
;             for (int e = 0; e < 4; ++e) {
;                 const int i = 8 * (s & 1) + 2 * e;
;                 f32x2 pv;
;                 pv.x = __builtin_amdgcn_exp2f(s < 2 ? S0[i] : S1[i]); pv.y = __builtin_amdgcn_exp2f(s < 2 ? S0[i + 1] : S1[i + 1]);
;                 ls2 = ls2 + pv;
;                 w[e] = pk2(pv.x, pv.y);
;             }
;             u32x4 wv; wv.x = w[0]; wv.y = w[1]; wv.z = w[2]; wv.w = w[3];
;             pf[s] = __builtin_bit_cast(bf16x8, wv);
;         }
;         l = l * alpha + (ls2.x + ls2.y);
;         if (__any(alpha != 1.0f)) {
; #pragma unroll
;             for (int blk = 0; blk < 4; ++blk) O[blk] = O[blk] * alpha;
;         }
;     };
;     auto pv_acc = [&](int st) __attribute__((always_inline)) {
;         LAS unsigned char* Vb = lds + st * A_STAGE;
; #pragma unroll
;         for (int s = 0; s < 4; ++s) {
; #pragma unroll
;             for (int blk = 0; blk < 4; ++blk) {
;                 const s16x4 lo = __builtin_amdgcn_ds_read_tr16_b64_v4i16((LAS s16x4*)(Vb + s * 4096 + voffs[blk][0]));
;                 const s16x4 hi = __builtin_amdgcn_ds_read_tr16_b64_v4i16((LAS s16x4*)(Vb + s * 4096 + voffs[blk][1]));
;                 const bf16x8 va = __builtin_shufflevector(lo, hi, 0, 1, 2, 3, 4, 5, 6, 7);
;                 O[blk] = MFMA32(va, pf[s], O[blk]);
;             }
;         }
.LBB0_466:
	v_pk_add_f32 v[92:93], v[96:97], v[0:1] op_sel_hi:[1,0] neg_lo:[0,1] neg_hi:[0,1]
	v_pk_add_f32 v[104:105], v[8:9], v[0:1] op_sel_hi:[1,0] neg_lo:[0,1] neg_hi:[0,1]
	v_exp_f32_e32 v8, v92
	v_exp_f32_e32 v9, v93
	v_pk_add_f32 v[96:97], v[98:99], v[0:1] op_sel_hi:[1,0] neg_lo:[0,1] neg_hi:[0,1]
	v_pk_add_f32 v[94:95], v[80:81], v[0:1] op_sel_hi:[1,0] neg_lo:[0,1] neg_hi:[0,1]
	v_pk_add_f32 v[98:99], v[82:83], v[0:1] op_sel_hi:[1,0] neg_lo:[0,1] neg_hi:[0,1]
	v_pk_add_f32 v[82:83], v[100:101], v[0:1] op_sel_hi:[1,0] neg_lo:[0,1] neg_hi:[0,1]
	v_pk_add_f32 v[100:101], v[102:103], v[0:1] op_sel_hi:[1,0] neg_lo:[0,1] neg_hi:[0,1]
	v_pk_add_f32 v[102:103], v[12:13], v[0:1] op_sel_hi:[1,0] neg_lo:[0,1] neg_hi:[0,1]
	v_pk_add_f32 v[12:13], v[8:9], 0 op_sel_hi:[1,0]
	v_cvt_pk_bf16_f32 v80, v8, v9
	v_exp_f32_e32 v8, v96
	v_exp_f32_e32 v9, v97
	v_pk_add_f32 v[10:11], v[10:11], v[0:1] op_sel_hi:[1,0] neg_lo:[0,1] neg_hi:[0,1]
	v_pk_add_f32 v[6:7], v[6:7], v[0:1] op_sel_hi:[1,0] neg_lo:[0,1] neg_hi:[0,1]
	v_pk_add_f32 v[4:5], v[4:5], v[0:1] op_sel_hi:[1,0] neg_lo:[0,1] neg_hi:[0,1]
	v_pk_add_f32 v[12:13], v[8:9], v[12:13]
	v_cvt_pk_bf16_f32 v81, v8, v9
	v_exp_f32_e32 v8, v82
	v_exp_f32_e32 v9, v83
	v_exp_f32_e32 v6, v6
	v_exp_f32_e32 v7, v7
	v_pk_add_f32 v[2:3], v[2:3], v[0:1] op_sel_hi:[1,0] neg_lo:[0,1] neg_hi:[0,1]
	v_pk_add_f32 v[12:13], v[8:9], v[12:13]
	v_cvt_pk_bf16_f32 v82, v8, v9
	v_exp_f32_e32 v8, v100
	v_exp_f32_e32 v9, v101
	v_exp_f32_e32 v4, v4
	v_exp_f32_e32 v5, v5
	v_exp_f32_e32 v2, v2
	v_pk_add_f32 v[12:13], v[8:9], v[12:13]
	v_cvt_pk_bf16_f32 v83, v8, v9
	v_exp_f32_e32 v8, v10
	v_exp_f32_e32 v9, v11
	v_exp_f32_e32 v3, v3
	v_cvt_pk_bf16_f32 v11, v6, v7
	v_pk_add_f32 v[84:85], v[84:85], v[0:1] op_sel_hi:[1,0] neg_lo:[0,1] neg_hi:[0,1]
	v_pk_add_f32 v[12:13], v[8:9], v[12:13]
	v_cvt_pk_bf16_f32 v10, v8, v9
	v_pk_add_f32 v[8:9], v[6:7], v[12:13]
	v_cvt_pk_bf16_f32 v12, v4, v5
	v_pk_add_f32 v[6:7], v[4:5], v[8:9]
	v_cvt_pk_bf16_f32 v13, v2, v3
	v_pk_add_f32 v[4:5], v[2:3], v[6:7]
	v_exp_f32_e32 v2, v94
	v_exp_f32_e32 v3, v95
	v_pk_add_f32 v[86:87], v[86:87], v[0:1] op_sel_hi:[1,0] neg_lo:[0,1] neg_hi:[0,1]
	v_pk_add_f32 v[88:89], v[88:89], v[0:1] op_sel_hi:[1,0] neg_lo:[0,1] neg_hi:[0,1]
	v_pk_add_f32 v[90:91], v[90:91], v[0:1] op_sel_hi:[1,0] neg_lo:[0,1] neg_hi:[0,1]
	v_pk_add_f32 v[4:5], v[2:3], v[4:5]
	v_cvt_pk_bf16_f32 v6, v2, v3
	v_exp_f32_e32 v2, v98
	v_exp_f32_e32 v3, v99
	v_add_u32_e32 v92, s51, v169
	v_add_u32_e32 v93, s51, v170
	v_add_u32_e32 v94, s51, v171
	v_pk_add_f32 v[4:5], v[2:3], v[4:5]
	v_cvt_pk_bf16_f32 v7, v2, v3
	v_exp_f32_e32 v2, v84
	v_exp_f32_e32 v3, v85
	v_exp_f32_e32 v84, v90
	v_exp_f32_e32 v85, v91
	v_add_u32_e32 v90, s51, v167
	v_pk_add_f32 v[4:5], v[2:3], v[4:5]
	v_cvt_pk_bf16_f32 v8, v2, v3
	v_exp_f32_e32 v2, v86
	v_exp_f32_e32 v3, v87
	v_add_u32_e32 v91, s51, v168
	v_pk_add_f32 v[4:5], v[2:3], v[4:5]
	v_cvt_pk_bf16_f32 v9, v2, v3
	v_exp_f32_e32 v2, v88
	v_exp_f32_e32 v3, v89
	v_add_u32_e32 v88, s51, v165
	v_add_u32_e32 v89, s51, v166
	v_pk_add_f32 v[4:5], v[2:3], v[4:5]
	v_cvt_pk_bf16_f32 v2, v2, v3
	v_pk_add_f32 v[4:5], v[84:85], v[4:5]
	v_cvt_pk_bf16_f32 v3, v84, v85
	v_exp_f32_e32 v84, v102
	v_exp_f32_e32 v85, v103
	s_nop 0
	v_pk_add_f32 v[86:87], v[84:85], v[4:5]
	v_cvt_pk_bf16_f32 v4, v84, v85
	v_exp_f32_e32 v84, v104
	v_exp_f32_e32 v85, v105
	s_nop 0
	v_pk_add_f32 v[86:87], v[84:85], v[86:87]
	s_nop 0
	v_add_f32_e32 v15, v86, v87
	v_fmac_f32_e32 v15, v174, v14
	v_add_u32_e32 v14, s51, v164
	v_cvt_pk_bf16_f32 v5, v84, v85
	s_waitcnt lgkmcnt(2)
	v_mfma_f32_32x32x16_bf16 v[64:79], v[192:195], v[80:83], v[64:79]
	ds_read_b64_tr_b16 v[192:193], v91 offset:16384
	ds_read_b64_tr_b16 v[194:195], v92 offset:2048
	v_mov_b32_e32 v174, v15
	s_waitcnt lgkmcnt(2)
	v_mfma_f32_32x32x16_bf16 v[48:63], v[196:199], v[80:83], v[48:63]
	ds_read_b64_tr_b16 v[196:197], v93 offset:16384
	ds_read_b64_tr_b16 v[198:199], v94 offset:2048
	s_waitcnt lgkmcnt(2)
	v_mfma_f32_32x32x16_bf16 v[32:47], v[192:195], v[80:83], v[32:47]
	ds_read_b64_tr_b16 v[192:193], v14 offset:20480
	ds_read_b64_tr_b16 v[194:195], v88 offset:6144
	s_waitcnt lgkmcnt(2)
	v_mfma_f32_32x32x16_bf16 v[16:31], v[196:199], v[80:83], v[16:31]
	ds_read_b64_tr_b16 v[196:197], v89 offset:20480
	ds_read_b64_tr_b16 v[198:199], v90 offset:6144
	s_waitcnt lgkmcnt(2)
	v_mfma_f32_32x32x16_bf16 v[64:79], v[192:195], v[10:13], v[64:79]
	ds_read_b64_tr_b16 v[192:193], v91 offset:20480
	ds_read_b64_tr_b16 v[194:195], v92 offset:6144
	s_waitcnt lgkmcnt(2)
	v_mfma_f32_32x32x16_bf16 v[48:63], v[196:199], v[10:13], v[48:63]
	ds_read_b64_tr_b16 v[196:197], v93 offset:20480
	ds_read_b64_tr_b16 v[198:199], v94 offset:6144
	s_waitcnt lgkmcnt(2)
	v_mfma_f32_32x32x16_bf16 v[32:47], v[192:195], v[10:13], v[32:47]
	ds_read_b64_tr_b16 v[192:193], v14 offset:24576
	ds_read_b64_tr_b16 v[194:195], v88 offset:10240
	s_waitcnt lgkmcnt(2)
	v_mfma_f32_32x32x16_bf16 v[16:31], v[196:199], v[10:13], v[16:31]
	ds_read_b64_tr_b16 v[196:197], v89 offset:24576
	ds_read_b64_tr_b16 v[198:199], v90 offset:10240
	s_waitcnt lgkmcnt(2)
	v_mfma_f32_32x32x16_bf16 v[64:79], v[192:195], v[6:9], v[64:79]
	ds_read_b64_tr_b16 v[192:193], v91 offset:24576
	ds_read_b64_tr_b16 v[194:195], v92 offset:10240
	s_waitcnt lgkmcnt(2)
	v_mfma_f32_32x32x16_bf16 v[48:63], v[196:199], v[6:9], v[48:63]
	ds_read_b64_tr_b16 v[196:197], v93 offset:24576
	ds_read_b64_tr_b16 v[198:199], v94 offset:10240
	s_waitcnt lgkmcnt(2)
	v_mfma_f32_32x32x16_bf16 v[32:47], v[192:195], v[6:9], v[32:47]
	ds_read_b64_tr_b16 v[192:193], v14 offset:28672
	ds_read_b64_tr_b16 v[194:195], v88 offset:14336
	s_waitcnt lgkmcnt(2)
	v_mfma_f32_32x32x16_bf16 v[16:31], v[196:199], v[6:9], v[16:31]
	ds_read_b64_tr_b16 v[196:197], v89 offset:28672
	ds_read_b64_tr_b16 v[198:199], v90 offset:14336
	s_waitcnt lgkmcnt(2)
	v_mfma_f32_32x32x16_bf16 v[64:79], v[192:195], v[2:5], v[64:79]
	ds_read_b64_tr_b16 v[192:193], v91 offset:28672
	ds_read_b64_tr_b16 v[194:195], v92 offset:14336
	s_waitcnt lgkmcnt(2)
	v_mfma_f32_32x32x16_bf16 v[48:63], v[196:199], v[2:5], v[48:63]
	ds_read_b64_tr_b16 v[196:197], v93 offset:28672
	ds_read_b64_tr_b16 v[198:199], v94 offset:14336
	s_waitcnt lgkmcnt(2)
	v_mfma_f32_32x32x16_bf16 v[32:47], v[192:195], v[2:5], v[32:47]
	s_waitcnt lgkmcnt(0)
	v_mfma_f32_32x32x16_bf16 v[16:31], v[196:199], v[2:5], v[16:31]
	s_cmp_ge_i32 s49, s45
	s_cbranch_scc0 .LBB0_468
	s_branch .LBB0_473
